# fourier item FFT (single-level pass loop): per-pass dispatch to a copy using A0+k*S leg addresses when stride >= 16
# speedup vs baseline: 1.0064x; 1.0027x over previous
; DI float sin_t(float turns) { return __builtin_amdgcn_sinf(__builtin_amdgcn_fractf(turns)); }
; DI float cos_t(float turns) { return __builtin_amdgcn_cosf(__builtin_amdgcn_fractf(turns)); }
; DI float2 cmul(float2 a, float2 b) { return make_float2(a.x * b.x - a.y * b.y, a.x * b.y + a.y * b.x); }
; template <int N, bool INV>
; DI void fft_lds(float2* s) {
;     ...
;     for (int lq = (LG & 1) ? LG - 3 : LG - 2; lq >= 0; lq -= 2) {
;       const int q = 1 << lq;
;       __syncthreads();
;       const float inv4q = 1.0f / (float)(4 * q);
; #pragma unroll 4
;       for (int it = 0; it < N / 4 / NT; ++it) {
;         int idx = tid + it * NT;
;         int j = idx & (q - 1), blk = idx >> lq;
;         int p0 = blk * 4 * q + j;
;         float f = (float)j * inv4q;
;         float2 t1 = make_float2(cos_t(f), -sin_t(f));
;         float2 t2 = cmul(t1, t1);
;         float2 x0 = s[phys(p0)], x1 = s[phys(p0 + q)], x2 = s[phys(p0 + 2 * q)], x3 = s[phys(p0 + 3 * q)];
;         float2 a0 = make_float2(x0.x + x2.x, x0.y + x2.y);
;         float2 a2 = cmul(make_float2(x0.x - x2.x, x0.y - x2.y), t1);
;         float2 a1 = make_float2(x1.x + x3.x, x1.y + x3.y);
;         float2 d3 = make_float2(x1.x - x3.x, x1.y - x3.y);
;         float2 a3 = cmul(make_float2(d3.y, -d3.x), t1);
;         s[phys(p0)] = make_float2(a0.x + a1.x, a0.y + a1.y);
;         s[phys(p0 + q)] = cmul(make_float2(a0.x - a1.x, a0.y - a1.y), t2);
;         s[phys(p0 + 2 * q)] = make_float2(a2.x + a3.x, a2.y + a3.y);
;         s[phys(p0 + 3 * q)] = cmul(make_float2(a2.x - a3.x, a2.y - a3.y), t2);
;       }
;     }
.LBB0_367:
	s_sub_i32 s32, s0, 4
	s_lshl_b32 s32, 0x88, s32
	s_cmp_lt_u32 s0, 4
	s_cbranch_scc0 .Lfft_fastb_367
	s_lshl_b32 s10, 4, s0
	v_cvt_f32_u32_e32 v5, s10
	s_lshl_b32 s1, 1, s0
	s_waitcnt lgkmcnt(0)
	s_barrier
	v_div_scale_f32 v6, s[10:11], v5, v5, 1.0
	v_rcp_f32_e32 v7, v6
	s_bfm_b32 s10, s0, 0
	v_and_b32_e32 v13, s10, v1
	v_fma_f32 v8, -v6, v7, 1.0
	v_fmac_f32_e32 v7, v8, v7
	v_div_scale_f32 v8, vcc, 1.0, v5, 1.0
	v_mul_f32_e32 v9, v8, v7
	v_fma_f32 v12, -v6, v9, v8
	v_fmac_f32_e32 v9, v12, v7
	v_fma_f32 v6, -v6, v9, v8
	v_div_fmas_f32 v6, v6, v7, v9
	v_div_fixup_f32 v5, v6, v5, 1.0
	v_ashrrev_i32_e32 v6, s0, v1
	v_lshlrev_b32_e32 v14, 2, v6
	v_lshl_add_u32 v15, v14, s0, v13
	v_ashrrev_i32_e32 v17, 4, v15
	v_add_lshl_u32 v17, v17, v15, 3
	v_add_u32_e32 v15, s1, v15
	v_cvt_f32_u32_e32 v6, v13
	v_ashrrev_i32_e32 v19, 4, v15
	v_add_lshl_u32 v19, v19, v15, 3
	v_or_b32_e32 v15, 2, v14
	v_or_b32_e32 v14, 3, v14
	v_lshl_add_u32 v15, v15, s0, v13
	v_lshl_add_u32 v13, v14, s0, v13
	v_mul_f32_e32 v6, v5, v6
	v_ashrrev_i32_e32 v20, 4, v15
	v_ashrrev_i32_e32 v14, 4, v13
	v_fract_f32_e32 v7, v6
	v_add_lshl_u32 v23, v20, v15, 3
	v_add_lshl_u32 v29, v14, v13, 3
	v_cos_f32_e32 v6, v7
	v_sin_f32_e32 v7, v7
	ds_read_b64 v[14:15], v17
	ds_read_b64 v[20:21], v19
	ds_read_b64 v[26:27], v23
	ds_read_b64 v[30:31], v29
	v_mov_b32_e32 v34, v7
	v_mul_f32_e64 v12, v6, -v7
	v_pk_mul_f32 v[8:9], v[6:7], v[6:7]
	s_waitcnt lgkmcnt(1)
	v_pk_add_f32 v[32:33], v[14:15], v[26:27] neg_lo:[0,1] neg_hi:[0,1]
	v_pk_add_f32 v[14:15], v[14:15], v[26:27]
	v_pk_mul_f32 v[36:37], v[34:35], v[32:33] op_sel_hi:[0,1]
	v_pk_fma_f32 v[40:41], v[6:7], v[32:33], v[36:37] op_sel:[0,0,1] op_sel_hi:[1,1,0]
	v_pk_fma_f32 v[32:33], v[6:7], v[32:33], v[36:37] op_sel:[0,0,1] op_sel_hi:[0,1,0] neg_lo:[0,0,1] neg_hi:[0,0,1]
	v_mov_b32_e32 v41, v33
	s_waitcnt lgkmcnt(0)
	v_pk_add_f32 v[32:33], v[20:21], v[30:31] neg_lo:[0,1] neg_hi:[0,1]
	v_pk_add_f32 v[20:21], v[20:21], v[30:31]
	v_add_f32_e32 v12, v12, v12
	v_pk_add_f32 v[26:27], v[14:15], v[20:21]
	v_pk_add_f32 v[14:15], v[14:15], v[20:21] neg_lo:[0,1] neg_hi:[0,1]
	v_xor_b32_e32 v37, 0x80000000, v32
	v_mov_b32_e32 v36, v33
	v_pk_mul_f32 v[32:33], v[34:35], v[32:33] op_sel_hi:[0,1]
	v_pk_mul_f32 v[20:21], v[12:13], v[14:15] op_sel_hi:[0,1]
	v_pk_add_f32 v[8:9], v[8:9], v[8:9] op_sel:[0,1] op_sel_hi:[0,1] neg_lo:[0,1] neg_hi:[0,1]
	v_pk_fma_f32 v[6:7], v[6:7], v[36:37], v[32:33] op_sel_hi:[0,1,1] neg_lo:[0,0,1] neg_hi:[0,0,1]
	ds_write_b64 v17, v[26:27]
	v_pk_fma_f32 v[26:27], v[8:9], v[14:15], v[20:21] op_sel:[0,0,1] op_sel_hi:[1,1,0] neg_lo:[0,0,1] neg_hi:[0,0,1]
	v_pk_fma_f32 v[14:15], v[8:9], v[14:15], v[20:21] op_sel:[0,0,1] op_sel_hi:[1,1,0]
	s_nop 0
	v_mov_b32_e32 v27, v15
	v_pk_add_f32 v[14:15], v[40:41], v[6:7]
	v_pk_add_f32 v[6:7], v[40:41], v[6:7] neg_lo:[0,1] neg_hi:[0,1]
	ds_write_b64 v19, v[26:27]
	v_pk_mul_f32 v[12:13], v[12:13], v[6:7] op_sel_hi:[0,1]
	ds_write_b64 v23, v[14:15]
	v_pk_fma_f32 v[14:15], v[8:9], v[6:7], v[12:13] op_sel:[0,0,1] op_sel_hi:[1,1,0] neg_lo:[0,0,1] neg_hi:[0,0,1]
	v_pk_fma_f32 v[6:7], v[8:9], v[6:7], v[12:13] op_sel:[0,0,1] op_sel_hi:[1,1,0]
	v_and_b32_e32 v13, s10, v2
	v_mov_b32_e32 v15, v7
	v_ashrrev_i32_e32 v6, s0, v2
	ds_write_b64 v29, v[14:15]
	v_lshlrev_b32_e32 v14, 2, v6
	v_lshl_add_u32 v15, v14, s0, v13
	v_ashrrev_i32_e32 v17, 4, v15
	v_add_lshl_u32 v17, v17, v15, 3
	v_add_u32_e32 v15, s1, v15
	v_cvt_f32_u32_e32 v6, v13
	v_ashrrev_i32_e32 v19, 4, v15
	v_add_lshl_u32 v19, v19, v15, 3
	v_or_b32_e32 v15, 2, v14
	v_or_b32_e32 v14, 3, v14
	v_lshl_add_u32 v15, v15, s0, v13
	v_lshl_add_u32 v13, v14, s0, v13
	v_mul_f32_e32 v6, v5, v6
	v_ashrrev_i32_e32 v20, 4, v15
	v_ashrrev_i32_e32 v14, 4, v13
	v_fract_f32_e32 v7, v6
	v_add_lshl_u32 v23, v20, v15, 3
	v_add_lshl_u32 v29, v14, v13, 3
	v_cos_f32_e32 v6, v7
	v_sin_f32_e32 v7, v7
	ds_read_b64 v[14:15], v17
	ds_read_b64 v[20:21], v19
	ds_read_b64 v[26:27], v23
	ds_read_b64 v[30:31], v29
	v_mov_b32_e32 v34, v7
	v_mul_f32_e64 v12, v6, -v7
	v_pk_mul_f32 v[8:9], v[6:7], v[6:7]
	s_waitcnt lgkmcnt(1)
	v_pk_add_f32 v[32:33], v[14:15], v[26:27] neg_lo:[0,1] neg_hi:[0,1]
	v_pk_add_f32 v[14:15], v[14:15], v[26:27]
	v_pk_mul_f32 v[36:37], v[34:35], v[32:33] op_sel_hi:[0,1]
	v_pk_fma_f32 v[40:41], v[6:7], v[32:33], v[36:37] op_sel:[0,0,1] op_sel_hi:[1,1,0]
	v_pk_fma_f32 v[32:33], v[6:7], v[32:33], v[36:37] op_sel:[0,0,1] op_sel_hi:[0,1,0] neg_lo:[0,0,1] neg_hi:[0,0,1]
	v_mov_b32_e32 v41, v33
	s_waitcnt lgkmcnt(0)
	v_pk_add_f32 v[32:33], v[20:21], v[30:31] neg_lo:[0,1] neg_hi:[0,1]
	v_pk_add_f32 v[20:21], v[20:21], v[30:31]
	v_add_f32_e32 v12, v12, v12
	v_pk_add_f32 v[26:27], v[14:15], v[20:21]
	v_pk_add_f32 v[14:15], v[14:15], v[20:21] neg_lo:[0,1] neg_hi:[0,1]
	v_xor_b32_e32 v37, 0x80000000, v32
	v_mov_b32_e32 v36, v33
	v_pk_mul_f32 v[32:33], v[34:35], v[32:33] op_sel_hi:[0,1]
	v_pk_mul_f32 v[20:21], v[12:13], v[14:15] op_sel_hi:[0,1]
	v_pk_add_f32 v[8:9], v[8:9], v[8:9] op_sel:[0,1] op_sel_hi:[0,1] neg_lo:[0,1] neg_hi:[0,1]
	v_pk_fma_f32 v[6:7], v[6:7], v[36:37], v[32:33] op_sel_hi:[0,1,1] neg_lo:[0,0,1] neg_hi:[0,0,1]
	ds_write_b64 v17, v[26:27]
	v_pk_fma_f32 v[26:27], v[8:9], v[14:15], v[20:21] op_sel:[0,0,1] op_sel_hi:[1,1,0] neg_lo:[0,0,1] neg_hi:[0,0,1]
	v_pk_fma_f32 v[14:15], v[8:9], v[14:15], v[20:21] op_sel:[0,0,1] op_sel_hi:[1,1,0]
	s_nop 0
	v_mov_b32_e32 v27, v15
	v_pk_add_f32 v[14:15], v[40:41], v[6:7]
	v_pk_add_f32 v[6:7], v[40:41], v[6:7] neg_lo:[0,1] neg_hi:[0,1]
	ds_write_b64 v19, v[26:27]
	v_pk_mul_f32 v[12:13], v[12:13], v[6:7] op_sel_hi:[0,1]
	ds_write_b64 v23, v[14:15]
	v_pk_fma_f32 v[14:15], v[8:9], v[6:7], v[12:13] op_sel:[0,0,1] op_sel_hi:[1,1,0] neg_lo:[0,0,1] neg_hi:[0,0,1]
	v_pk_fma_f32 v[6:7], v[8:9], v[6:7], v[12:13] op_sel:[0,0,1] op_sel_hi:[1,1,0]
	v_and_b32_e32 v13, s10, v3
	v_mov_b32_e32 v15, v7
	v_ashrrev_i32_e32 v6, s0, v3
	ds_write_b64 v29, v[14:15]
	v_lshlrev_b32_e32 v14, 2, v6
	v_lshl_add_u32 v15, v14, s0, v13
	v_ashrrev_i32_e32 v17, 4, v15
	v_add_lshl_u32 v17, v17, v15, 3
	v_add_u32_e32 v15, s1, v15
	v_cvt_f32_u32_e32 v6, v13
	v_ashrrev_i32_e32 v19, 4, v15
	v_add_lshl_u32 v19, v19, v15, 3
	v_or_b32_e32 v15, 2, v14
	v_or_b32_e32 v14, 3, v14
	v_lshl_add_u32 v15, v15, s0, v13
	v_lshl_add_u32 v13, v14, s0, v13
	v_mul_f32_e32 v6, v5, v6
	v_ashrrev_i32_e32 v20, 4, v15
	v_ashrrev_i32_e32 v14, 4, v13
	v_fract_f32_e32 v7, v6
	v_add_lshl_u32 v23, v20, v15, 3
	v_add_lshl_u32 v29, v14, v13, 3
	v_cos_f32_e32 v6, v7
	v_sin_f32_e32 v7, v7
	ds_read_b64 v[14:15], v17
	ds_read_b64 v[20:21], v19
	ds_read_b64 v[26:27], v23
	ds_read_b64 v[30:31], v29
	v_mov_b32_e32 v34, v7
	v_mul_f32_e64 v12, v6, -v7
	v_pk_mul_f32 v[8:9], v[6:7], v[6:7]
	s_waitcnt lgkmcnt(1)
; DI float sin_t(float turns) { return __builtin_amdgcn_sinf(__builtin_amdgcn_fractf(turns)); }
; DI float cos_t(float turns) { return __builtin_amdgcn_cosf(__builtin_amdgcn_fractf(turns)); }
; DI float2 cmul(float2 a, float2 b) { return make_float2(a.x * b.x - a.y * b.y, a.x * b.y + a.y * b.x); }
; template <int N, bool INV>
; DI void fft_lds(float2* s) {
;     ...
;     for (int lq = (LG & 1) ? LG - 3 : LG - 2; lq >= 0; lq -= 2) {
;       const int q = 1 << lq;
;       __syncthreads();
;       const float inv4q = 1.0f / (float)(4 * q);
; #pragma unroll 4
;       for (int it = 0; it < N / 4 / NT; ++it) {
;         int idx = tid + it * NT;
;         int j = idx & (q - 1), blk = idx >> lq;
;         int p0 = blk * 4 * q + j;
;         float f = (float)j * inv4q;
;         float2 t1 = make_float2(cos_t(f), -sin_t(f));
;         float2 t2 = cmul(t1, t1);
;         float2 x0 = s[phys(p0)], x1 = s[phys(p0 + q)], x2 = s[phys(p0 + 2 * q)], x3 = s[phys(p0 + 3 * q)];
;         float2 a0 = make_float2(x0.x + x2.x, x0.y + x2.y);
;         float2 a2 = cmul(make_float2(x0.x - x2.x, x0.y - x2.y), t1);
;         float2 a1 = make_float2(x1.x + x3.x, x1.y + x3.y);
;         float2 d3 = make_float2(x1.x - x3.x, x1.y - x3.y);
;         float2 a3 = cmul(make_float2(d3.y, -d3.x), t1);
;         s[phys(p0)] = make_float2(a0.x + a1.x, a0.y + a1.y);
;         s[phys(p0 + q)] = cmul(make_float2(a0.x - a1.x, a0.y - a1.y), t2);
;         s[phys(p0 + 2 * q)] = make_float2(a2.x + a3.x, a2.y + a3.y);
;         s[phys(p0 + 3 * q)] = cmul(make_float2(a2.x - a3.x, a2.y - a3.y), t2);
;       }
;     }
	v_pk_add_f32 v[32:33], v[14:15], v[26:27] neg_lo:[0,1] neg_hi:[0,1]
	v_pk_add_f32 v[14:15], v[14:15], v[26:27]
	v_pk_mul_f32 v[36:37], v[34:35], v[32:33] op_sel_hi:[0,1]
	v_pk_fma_f32 v[40:41], v[6:7], v[32:33], v[36:37] op_sel:[0,0,1] op_sel_hi:[1,1,0]
	v_pk_fma_f32 v[32:33], v[6:7], v[32:33], v[36:37] op_sel:[0,0,1] op_sel_hi:[0,1,0] neg_lo:[0,0,1] neg_hi:[0,0,1]
	v_mov_b32_e32 v41, v33
	s_waitcnt lgkmcnt(0)
	v_pk_add_f32 v[32:33], v[20:21], v[30:31] neg_lo:[0,1] neg_hi:[0,1]
	v_pk_add_f32 v[20:21], v[20:21], v[30:31]
	v_add_f32_e32 v12, v12, v12
	v_pk_add_f32 v[26:27], v[14:15], v[20:21]
	v_pk_add_f32 v[14:15], v[14:15], v[20:21] neg_lo:[0,1] neg_hi:[0,1]
	v_xor_b32_e32 v37, 0x80000000, v32
	v_mov_b32_e32 v36, v33
	v_pk_mul_f32 v[32:33], v[34:35], v[32:33] op_sel_hi:[0,1]
	v_pk_mul_f32 v[20:21], v[12:13], v[14:15] op_sel_hi:[0,1]
	v_pk_add_f32 v[8:9], v[8:9], v[8:9] op_sel:[0,1] op_sel_hi:[0,1] neg_lo:[0,1] neg_hi:[0,1]
	v_pk_fma_f32 v[6:7], v[6:7], v[36:37], v[32:33] op_sel_hi:[0,1,1] neg_lo:[0,0,1] neg_hi:[0,0,1]
	ds_write_b64 v17, v[26:27]
	v_pk_fma_f32 v[26:27], v[8:9], v[14:15], v[20:21] op_sel:[0,0,1] op_sel_hi:[1,1,0] neg_lo:[0,0,1] neg_hi:[0,0,1]
	v_pk_fma_f32 v[14:15], v[8:9], v[14:15], v[20:21] op_sel:[0,0,1] op_sel_hi:[1,1,0]
	s_nop 0
	v_mov_b32_e32 v27, v15
	v_pk_add_f32 v[14:15], v[40:41], v[6:7]
	v_pk_add_f32 v[6:7], v[40:41], v[6:7] neg_lo:[0,1] neg_hi:[0,1]
	ds_write_b64 v19, v[26:27]
	v_pk_mul_f32 v[12:13], v[12:13], v[6:7] op_sel_hi:[0,1]
	ds_write_b64 v23, v[14:15]
	v_pk_fma_f32 v[14:15], v[8:9], v[6:7], v[12:13] op_sel:[0,0,1] op_sel_hi:[1,1,0] neg_lo:[0,0,1] neg_hi:[0,0,1]
	v_pk_fma_f32 v[6:7], v[8:9], v[6:7], v[12:13] op_sel:[0,0,1] op_sel_hi:[1,1,0]
	s_nop 0
	v_and_b32_e32 v6, s10, v4
	v_cvt_f32_u32_e32 v8, v6
	v_mov_b32_e32 v15, v7
	v_ashrrev_i32_e32 v7, s0, v4
	v_lshlrev_b32_e32 v7, 2, v7
	v_mul_f32_e32 v5, v5, v8
	v_fract_f32_e32 v5, v5
	v_cos_f32_e32 v8, v5
	v_sin_f32_e32 v9, v5
	ds_write_b64 v29, v[14:15]
	v_lshl_add_u32 v15, v7, s0, v6
	v_mul_f32_e64 v5, v8, -v9
	v_add_f32_e32 v14, v5, v5
	v_ashrrev_i32_e32 v5, 4, v15
	v_add_lshl_u32 v5, v5, v15, 3
	v_add_u32_e32 v15, s1, v15
	v_ashrrev_i32_e32 v17, 4, v15
	v_lshlrev_b32_e32 v17, 3, v17
	v_lshlrev_b32_e32 v15, 3, v15
	v_add3_u32 v15, 0, v17, v15
	v_or_b32_e32 v17, 2, v7
	v_or_b32_e32 v7, 3, v7
	v_lshl_add_u32 v17, v17, s0, v6
	v_lshl_add_u32 v6, v7, s0, v6
	v_ashrrev_i32_e32 v19, 4, v17
	v_ashrrev_i32_e32 v7, 4, v6
	v_lshlrev_b32_e32 v19, 3, v19
	v_lshlrev_b32_e32 v17, 3, v17
	v_lshlrev_b32_e32 v7, 3, v7
	v_lshlrev_b32_e32 v6, 3, v6
	v_add3_u32 v17, 0, v19, v17
	v_add3_u32 v19, 0, v7, v6
	ds_read_b64 v[6:7], v5
	ds_read_b64 v[20:21], v15
	ds_read_b64 v[26:27], v17
	ds_read_b64 v[30:31], v19
	v_mov_b32_e32 v34, v9
	v_pk_mul_f32 v[12:13], v[8:9], v[8:9]
	s_add_i32 s0, s0, -2
	s_waitcnt lgkmcnt(1)
	v_pk_add_f32 v[32:33], v[6:7], v[26:27] neg_lo:[0,1] neg_hi:[0,1]
	v_pk_add_f32 v[6:7], v[6:7], v[26:27]
	v_pk_mul_f32 v[36:37], v[34:35], v[32:33] op_sel_hi:[0,1]
	v_pk_fma_f32 v[40:41], v[8:9], v[32:33], v[36:37] op_sel:[0,0,1] op_sel_hi:[1,1,0]
	v_pk_fma_f32 v[32:33], v[8:9], v[32:33], v[36:37] op_sel:[0,0,1] op_sel_hi:[0,1,0] neg_lo:[0,0,1] neg_hi:[0,0,1]
	v_mov_b32_e32 v41, v33
	s_waitcnt lgkmcnt(0)
	v_pk_add_f32 v[32:33], v[20:21], v[30:31] neg_lo:[0,1] neg_hi:[0,1]
	v_pk_add_f32 v[20:21], v[20:21], v[30:31]
	v_xor_b32_e32 v37, 0x80000000, v32
	v_pk_add_f32 v[26:27], v[6:7], v[20:21]
	v_pk_add_f32 v[6:7], v[6:7], v[20:21] neg_lo:[0,1] neg_hi:[0,1]
	v_mov_b32_e32 v36, v33
	v_pk_mul_f32 v[32:33], v[34:35], v[32:33] op_sel_hi:[0,1]
	v_pk_mul_f32 v[20:21], v[14:15], v[6:7] op_sel_hi:[0,1]
	v_pk_add_f32 v[12:13], v[12:13], v[12:13] op_sel:[0,1] op_sel_hi:[0,1] neg_lo:[0,1] neg_hi:[0,1]
	v_pk_fma_f32 v[8:9], v[8:9], v[36:37], v[32:33] op_sel_hi:[0,1,1] neg_lo:[0,0,1] neg_hi:[0,0,1]
	ds_write_b64 v5, v[26:27]
	v_pk_fma_f32 v[26:27], v[12:13], v[6:7], v[20:21] op_sel:[0,0,1] op_sel_hi:[1,1,0] neg_lo:[0,0,1] neg_hi:[0,0,1]
	v_pk_fma_f32 v[6:7], v[12:13], v[6:7], v[20:21] op_sel:[0,0,1] op_sel_hi:[1,1,0]
	s_cmp_lg_u32 s0, -2
	v_mov_b32_e32 v27, v7
	v_pk_add_f32 v[6:7], v[40:41], v[8:9]
	ds_write_b64 v15, v[26:27]
	ds_write_b64 v17, v[6:7]
	v_pk_add_f32 v[6:7], v[40:41], v[8:9] neg_lo:[0,1] neg_hi:[0,1]
	s_nop 0
	v_pk_mul_f32 v[8:9], v[14:15], v[6:7] op_sel_hi:[0,1]
	v_pk_fma_f32 v[14:15], v[12:13], v[6:7], v[8:9] op_sel:[0,0,1] op_sel_hi:[1,1,0] neg_lo:[0,0,1] neg_hi:[0,0,1]
	v_pk_fma_f32 v[6:7], v[12:13], v[6:7], v[8:9] op_sel:[0,0,1] op_sel_hi:[1,1,0]
	s_nop 0
	v_mov_b32_e32 v15, v7
	ds_write_b64 v19, v[14:15]
	s_cbranch_scc1 .LBB0_367
	s_branch .Lfft_doneb_367
; DI float sin_t(float turns) { return __builtin_amdgcn_sinf(__builtin_amdgcn_fractf(turns)); }
; DI float cos_t(float turns) { return __builtin_amdgcn_cosf(__builtin_amdgcn_fractf(turns)); }
; DI float2 cmul(float2 a, float2 b) { return make_float2(a.x * b.x - a.y * b.y, a.x * b.y + a.y * b.x); }
; template <int N, bool INV>
; DI void fft_lds(float2* s) {
;     ...
;     for (int lq = (LG & 1) ? LG - 3 : LG - 2; lq >= 0; lq -= 2) {
;       const int q = 1 << lq;
;       __syncthreads();
;       const float inv4q = 1.0f / (float)(4 * q);
; #pragma unroll 4
;       for (int it = 0; it < N / 4 / NT; ++it) {
;         int idx = tid + it * NT;
;         int j = idx & (q - 1), blk = idx >> lq;
;         int p0 = blk * 4 * q + j;
;         float f = (float)j * inv4q;
;         float2 t1 = make_float2(cos_t(f), -sin_t(f));
;         float2 t2 = cmul(t1, t1);
;         float2 x0 = s[phys(p0)], x1 = s[phys(p0 + q)], x2 = s[phys(p0 + 2 * q)], x3 = s[phys(p0 + 3 * q)];
;         float2 a0 = make_float2(x0.x + x2.x, x0.y + x2.y);
;         float2 a2 = cmul(make_float2(x0.x - x2.x, x0.y - x2.y), t1);
;         float2 a1 = make_float2(x1.x + x3.x, x1.y + x3.y);
;         float2 d3 = make_float2(x1.x - x3.x, x1.y - x3.y);
;         float2 a3 = cmul(make_float2(d3.y, -d3.x), t1);
;         s[phys(p0)] = make_float2(a0.x + a1.x, a0.y + a1.y);
;         s[phys(p0 + q)] = cmul(make_float2(a0.x - a1.x, a0.y - a1.y), t2);
;         s[phys(p0 + 2 * q)] = make_float2(a2.x + a3.x, a2.y + a3.y);
;         s[phys(p0 + 3 * q)] = cmul(make_float2(a2.x - a3.x, a2.y - a3.y), t2);
;       }
;     }
.Lfft_fastb_367:
	s_lshl_b32 s10, 4, s0
	v_cvt_f32_u32_e32 v5, s10
	s_lshl_b32 s1, 1, s0
	s_waitcnt lgkmcnt(0)
	s_barrier
	v_div_scale_f32 v6, s[10:11], v5, v5, 1.0
	v_rcp_f32_e32 v7, v6
	s_bfm_b32 s10, s0, 0
	v_and_b32_e32 v13, s10, v1
	v_fma_f32 v8, -v6, v7, 1.0
	v_fmac_f32_e32 v7, v8, v7
	v_div_scale_f32 v8, vcc, 1.0, v5, 1.0
	v_mul_f32_e32 v9, v8, v7
	v_fma_f32 v12, -v6, v9, v8
	v_fmac_f32_e32 v9, v12, v7
	v_fma_f32 v6, -v6, v9, v8
	v_div_fmas_f32 v6, v6, v7, v9
	v_div_fixup_f32 v5, v6, v5, 1.0
	v_ashrrev_i32_e32 v6, s0, v1
	v_lshlrev_b32_e32 v14, 2, v6
	v_lshl_add_u32 v15, v14, s0, v13
	v_ashrrev_i32_e32 v17, 4, v15
	v_add_lshl_u32 v17, v17, v15, 3
	v_cvt_f32_u32_e32 v6, v13
	v_mul_f32_e32 v6, v5, v6
	v_fract_f32_e32 v7, v6
	v_add_u32_e32 v19, s32, v17
	v_add_u32_e32 v23, s32, v19
	v_add_u32_e32 v29, s32, v23
	v_cos_f32_e32 v6, v7
	v_sin_f32_e32 v7, v7
	ds_read_b64 v[14:15], v17
	ds_read_b64 v[20:21], v19
	ds_read_b64 v[26:27], v23
	ds_read_b64 v[30:31], v29
	v_mov_b32_e32 v34, v7
	v_mul_f32_e64 v12, v6, -v7
	v_pk_mul_f32 v[8:9], v[6:7], v[6:7]
	s_waitcnt lgkmcnt(1)
	v_pk_add_f32 v[32:33], v[14:15], v[26:27] neg_lo:[0,1] neg_hi:[0,1]
	v_pk_add_f32 v[14:15], v[14:15], v[26:27]
	v_pk_mul_f32 v[36:37], v[34:35], v[32:33] op_sel_hi:[0,1]
	v_pk_fma_f32 v[40:41], v[6:7], v[32:33], v[36:37] op_sel:[0,0,1] op_sel_hi:[1,1,0]
	v_pk_fma_f32 v[32:33], v[6:7], v[32:33], v[36:37] op_sel:[0,0,1] op_sel_hi:[0,1,0] neg_lo:[0,0,1] neg_hi:[0,0,1]
	v_mov_b32_e32 v41, v33
	s_waitcnt lgkmcnt(0)
	v_pk_add_f32 v[32:33], v[20:21], v[30:31] neg_lo:[0,1] neg_hi:[0,1]
	v_pk_add_f32 v[20:21], v[20:21], v[30:31]
	v_add_f32_e32 v12, v12, v12
	v_pk_add_f32 v[26:27], v[14:15], v[20:21]
	v_pk_add_f32 v[14:15], v[14:15], v[20:21] neg_lo:[0,1] neg_hi:[0,1]
	v_xor_b32_e32 v37, 0x80000000, v32
	v_mov_b32_e32 v36, v33
	v_pk_mul_f32 v[32:33], v[34:35], v[32:33] op_sel_hi:[0,1]
	v_pk_mul_f32 v[20:21], v[12:13], v[14:15] op_sel_hi:[0,1]
	v_pk_add_f32 v[8:9], v[8:9], v[8:9] op_sel:[0,1] op_sel_hi:[0,1] neg_lo:[0,1] neg_hi:[0,1]
	v_pk_fma_f32 v[6:7], v[6:7], v[36:37], v[32:33] op_sel_hi:[0,1,1] neg_lo:[0,0,1] neg_hi:[0,0,1]
	ds_write_b64 v17, v[26:27]
	v_pk_fma_f32 v[26:27], v[8:9], v[14:15], v[20:21] op_sel:[0,0,1] op_sel_hi:[1,1,0] neg_lo:[0,0,1] neg_hi:[0,0,1]
	v_pk_fma_f32 v[14:15], v[8:9], v[14:15], v[20:21] op_sel:[0,0,1] op_sel_hi:[1,1,0]
	s_nop 0
	v_mov_b32_e32 v27, v15
	v_pk_add_f32 v[14:15], v[40:41], v[6:7]
	v_pk_add_f32 v[6:7], v[40:41], v[6:7] neg_lo:[0,1] neg_hi:[0,1]
	ds_write_b64 v19, v[26:27]
	v_pk_mul_f32 v[12:13], v[12:13], v[6:7] op_sel_hi:[0,1]
	ds_write_b64 v23, v[14:15]
	v_pk_fma_f32 v[14:15], v[8:9], v[6:7], v[12:13] op_sel:[0,0,1] op_sel_hi:[1,1,0] neg_lo:[0,0,1] neg_hi:[0,0,1]
	v_pk_fma_f32 v[6:7], v[8:9], v[6:7], v[12:13] op_sel:[0,0,1] op_sel_hi:[1,1,0]
	v_and_b32_e32 v13, s10, v2
	v_mov_b32_e32 v15, v7
	v_ashrrev_i32_e32 v6, s0, v2
	ds_write_b64 v29, v[14:15]
	v_lshlrev_b32_e32 v14, 2, v6
	v_lshl_add_u32 v15, v14, s0, v13
	v_ashrrev_i32_e32 v17, 4, v15
	v_add_lshl_u32 v17, v17, v15, 3
	v_cvt_f32_u32_e32 v6, v13
	v_mul_f32_e32 v6, v5, v6
	v_fract_f32_e32 v7, v6
	v_add_u32_e32 v19, s32, v17
	v_add_u32_e32 v23, s32, v19
	v_add_u32_e32 v29, s32, v23
	v_cos_f32_e32 v6, v7
	v_sin_f32_e32 v7, v7
	ds_read_b64 v[14:15], v17
	ds_read_b64 v[20:21], v19
	ds_read_b64 v[26:27], v23
	ds_read_b64 v[30:31], v29
	v_mov_b32_e32 v34, v7
	v_mul_f32_e64 v12, v6, -v7
	v_pk_mul_f32 v[8:9], v[6:7], v[6:7]
	s_waitcnt lgkmcnt(1)
	v_pk_add_f32 v[32:33], v[14:15], v[26:27] neg_lo:[0,1] neg_hi:[0,1]
	v_pk_add_f32 v[14:15], v[14:15], v[26:27]
	v_pk_mul_f32 v[36:37], v[34:35], v[32:33] op_sel_hi:[0,1]
	v_pk_fma_f32 v[40:41], v[6:7], v[32:33], v[36:37] op_sel:[0,0,1] op_sel_hi:[1,1,0]
	v_pk_fma_f32 v[32:33], v[6:7], v[32:33], v[36:37] op_sel:[0,0,1] op_sel_hi:[0,1,0] neg_lo:[0,0,1] neg_hi:[0,0,1]
	v_mov_b32_e32 v41, v33
	s_waitcnt lgkmcnt(0)
	v_pk_add_f32 v[32:33], v[20:21], v[30:31] neg_lo:[0,1] neg_hi:[0,1]
	v_pk_add_f32 v[20:21], v[20:21], v[30:31]
	v_add_f32_e32 v12, v12, v12
	v_pk_add_f32 v[26:27], v[14:15], v[20:21]
	v_pk_add_f32 v[14:15], v[14:15], v[20:21] neg_lo:[0,1] neg_hi:[0,1]
	v_xor_b32_e32 v37, 0x80000000, v32
	v_mov_b32_e32 v36, v33
	v_pk_mul_f32 v[32:33], v[34:35], v[32:33] op_sel_hi:[0,1]
	v_pk_mul_f32 v[20:21], v[12:13], v[14:15] op_sel_hi:[0,1]
	v_pk_add_f32 v[8:9], v[8:9], v[8:9] op_sel:[0,1] op_sel_hi:[0,1] neg_lo:[0,1] neg_hi:[0,1]
	v_pk_fma_f32 v[6:7], v[6:7], v[36:37], v[32:33] op_sel_hi:[0,1,1] neg_lo:[0,0,1] neg_hi:[0,0,1]
	ds_write_b64 v17, v[26:27]
	v_pk_fma_f32 v[26:27], v[8:9], v[14:15], v[20:21] op_sel:[0,0,1] op_sel_hi:[1,1,0] neg_lo:[0,0,1] neg_hi:[0,0,1]
	v_pk_fma_f32 v[14:15], v[8:9], v[14:15], v[20:21] op_sel:[0,0,1] op_sel_hi:[1,1,0]
	s_nop 0
	v_mov_b32_e32 v27, v15
	v_pk_add_f32 v[14:15], v[40:41], v[6:7]
	v_pk_add_f32 v[6:7], v[40:41], v[6:7] neg_lo:[0,1] neg_hi:[0,1]
	ds_write_b64 v19, v[26:27]
	v_pk_mul_f32 v[12:13], v[12:13], v[6:7] op_sel_hi:[0,1]
	ds_write_b64 v23, v[14:15]
	v_pk_fma_f32 v[14:15], v[8:9], v[6:7], v[12:13] op_sel:[0,0,1] op_sel_hi:[1,1,0] neg_lo:[0,0,1] neg_hi:[0,0,1]
	v_pk_fma_f32 v[6:7], v[8:9], v[6:7], v[12:13] op_sel:[0,0,1] op_sel_hi:[1,1,0]
	v_and_b32_e32 v13, s10, v3
	v_mov_b32_e32 v15, v7
	v_ashrrev_i32_e32 v6, s0, v3
	ds_write_b64 v29, v[14:15]
	v_lshlrev_b32_e32 v14, 2, v6
	v_lshl_add_u32 v15, v14, s0, v13
	v_ashrrev_i32_e32 v17, 4, v15
	v_add_lshl_u32 v17, v17, v15, 3
	v_cvt_f32_u32_e32 v6, v13
	v_mul_f32_e32 v6, v5, v6
	v_fract_f32_e32 v7, v6
	v_add_u32_e32 v19, s32, v17
	v_add_u32_e32 v23, s32, v19
	v_add_u32_e32 v29, s32, v23
	v_cos_f32_e32 v6, v7
	v_sin_f32_e32 v7, v7
	ds_read_b64 v[14:15], v17
	ds_read_b64 v[20:21], v19
	ds_read_b64 v[26:27], v23
	ds_read_b64 v[30:31], v29
	v_mov_b32_e32 v34, v7
	v_mul_f32_e64 v12, v6, -v7
	v_pk_mul_f32 v[8:9], v[6:7], v[6:7]
	s_waitcnt lgkmcnt(1)
; DI float sin_t(float turns) { return __builtin_amdgcn_sinf(__builtin_amdgcn_fractf(turns)); }
; DI float cos_t(float turns) { return __builtin_amdgcn_cosf(__builtin_amdgcn_fractf(turns)); }
; DI float2 cmul(float2 a, float2 b) { return make_float2(a.x * b.x - a.y * b.y, a.x * b.y + a.y * b.x); }
; template <int N, bool INV>
; DI void fft_lds(float2* s) {
;     ...
;       __syncthreads();
;       constexpr int h = N / 2;
; #pragma unroll 4
;       for (int j = tid; j < h; j += NT) {
;         float f = (float)j * (1.0f / N);
;         float2 w = make_float2(cos_t(f), -sin_t(f));
;         float2 a = s[phys(j)], b = s[phys(j + h)];
;     ...
;     for (int lq = (LG & 1) ? LG - 3 : LG - 2; lq >= 0; lq -= 2) {
;       const int q = 1 << lq;
;       __syncthreads();
;       const float inv4q = 1.0f / (float)(4 * q);
; #pragma unroll 4
;       for (int it = 0; it < N / 4 / NT; ++it) {
;         int idx = tid + it * NT;
;         int j = idx & (q - 1), blk = idx >> lq;
;         int p0 = blk * 4 * q + j;
;         float f = (float)j * inv4q;
;         float2 t1 = make_float2(cos_t(f), -sin_t(f));
;         float2 t2 = cmul(t1, t1);
;         float2 x0 = s[phys(p0)], x1 = s[phys(p0 + q)], x2 = s[phys(p0 + 2 * q)], x3 = s[phys(p0 + 3 * q)];
;         float2 a0 = make_float2(x0.x + x2.x, x0.y + x2.y);
;         float2 a2 = cmul(make_float2(x0.x - x2.x, x0.y - x2.y), t1);
;         float2 a1 = make_float2(x1.x + x3.x, x1.y + x3.y);
;         float2 d3 = make_float2(x1.x - x3.x, x1.y - x3.y);
;         float2 a3 = cmul(make_float2(d3.y, -d3.x), t1);
;         s[phys(p0)] = make_float2(a0.x + a1.x, a0.y + a1.y);
;         s[phys(p0 + q)] = cmul(make_float2(a0.x - a1.x, a0.y - a1.y), t2);
;         s[phys(p0 + 2 * q)] = make_float2(a2.x + a3.x, a2.y + a3.y);
;         s[phys(p0 + 3 * q)] = cmul(make_float2(a2.x - a3.x, a2.y - a3.y), t2);
;       }
;     }
	v_pk_add_f32 v[32:33], v[14:15], v[26:27] neg_lo:[0,1] neg_hi:[0,1]
	v_pk_add_f32 v[14:15], v[14:15], v[26:27]
	v_pk_mul_f32 v[36:37], v[34:35], v[32:33] op_sel_hi:[0,1]
	v_pk_fma_f32 v[40:41], v[6:7], v[32:33], v[36:37] op_sel:[0,0,1] op_sel_hi:[1,1,0]
	v_pk_fma_f32 v[32:33], v[6:7], v[32:33], v[36:37] op_sel:[0,0,1] op_sel_hi:[0,1,0] neg_lo:[0,0,1] neg_hi:[0,0,1]
	v_mov_b32_e32 v41, v33
	s_waitcnt lgkmcnt(0)
	v_pk_add_f32 v[32:33], v[20:21], v[30:31] neg_lo:[0,1] neg_hi:[0,1]
	v_pk_add_f32 v[20:21], v[20:21], v[30:31]
	v_add_f32_e32 v12, v12, v12
	v_pk_add_f32 v[26:27], v[14:15], v[20:21]
	v_pk_add_f32 v[14:15], v[14:15], v[20:21] neg_lo:[0,1] neg_hi:[0,1]
	v_xor_b32_e32 v37, 0x80000000, v32
	v_mov_b32_e32 v36, v33
	v_pk_mul_f32 v[32:33], v[34:35], v[32:33] op_sel_hi:[0,1]
	v_pk_mul_f32 v[20:21], v[12:13], v[14:15] op_sel_hi:[0,1]
	v_pk_add_f32 v[8:9], v[8:9], v[8:9] op_sel:[0,1] op_sel_hi:[0,1] neg_lo:[0,1] neg_hi:[0,1]
	v_pk_fma_f32 v[6:7], v[6:7], v[36:37], v[32:33] op_sel_hi:[0,1,1] neg_lo:[0,0,1] neg_hi:[0,0,1]
	ds_write_b64 v17, v[26:27]
	v_pk_fma_f32 v[26:27], v[8:9], v[14:15], v[20:21] op_sel:[0,0,1] op_sel_hi:[1,1,0] neg_lo:[0,0,1] neg_hi:[0,0,1]
	v_pk_fma_f32 v[14:15], v[8:9], v[14:15], v[20:21] op_sel:[0,0,1] op_sel_hi:[1,1,0]
	s_nop 0
	v_mov_b32_e32 v27, v15
	v_pk_add_f32 v[14:15], v[40:41], v[6:7]
	v_pk_add_f32 v[6:7], v[40:41], v[6:7] neg_lo:[0,1] neg_hi:[0,1]
	ds_write_b64 v19, v[26:27]
	v_pk_mul_f32 v[12:13], v[12:13], v[6:7] op_sel_hi:[0,1]
	ds_write_b64 v23, v[14:15]
	v_pk_fma_f32 v[14:15], v[8:9], v[6:7], v[12:13] op_sel:[0,0,1] op_sel_hi:[1,1,0] neg_lo:[0,0,1] neg_hi:[0,0,1]
	v_pk_fma_f32 v[6:7], v[8:9], v[6:7], v[12:13] op_sel:[0,0,1] op_sel_hi:[1,1,0]
	s_nop 0
	v_and_b32_e32 v6, s10, v4
	v_cvt_f32_u32_e32 v8, v6
	v_mov_b32_e32 v15, v7
	v_ashrrev_i32_e32 v7, s0, v4
	v_lshlrev_b32_e32 v7, 2, v7
	v_mul_f32_e32 v5, v5, v8
	v_fract_f32_e32 v5, v5
	v_cos_f32_e32 v8, v5
	v_sin_f32_e32 v9, v5
	ds_write_b64 v29, v[14:15]
	v_lshl_add_u32 v15, v7, s0, v6
	v_mul_f32_e64 v5, v8, -v9
	v_add_f32_e32 v14, v5, v5
	v_ashrrev_i32_e32 v5, 4, v15
	v_add_lshl_u32 v5, v5, v15, 3
	v_add_u32_e32 v15, s32, v5
	v_add_u32_e32 v17, s32, v15
	v_add_u32_e32 v19, s32, v17
	ds_read_b64 v[6:7], v5
	ds_read_b64 v[20:21], v15
	ds_read_b64 v[26:27], v17
	ds_read_b64 v[30:31], v19
	v_mov_b32_e32 v34, v9
	v_pk_mul_f32 v[12:13], v[8:9], v[8:9]
	s_add_i32 s0, s0, -2
	s_waitcnt lgkmcnt(1)
	v_pk_add_f32 v[32:33], v[6:7], v[26:27] neg_lo:[0,1] neg_hi:[0,1]
	v_pk_add_f32 v[6:7], v[6:7], v[26:27]
	v_pk_mul_f32 v[36:37], v[34:35], v[32:33] op_sel_hi:[0,1]
	v_pk_fma_f32 v[40:41], v[8:9], v[32:33], v[36:37] op_sel:[0,0,1] op_sel_hi:[1,1,0]
	v_pk_fma_f32 v[32:33], v[8:9], v[32:33], v[36:37] op_sel:[0,0,1] op_sel_hi:[0,1,0] neg_lo:[0,0,1] neg_hi:[0,0,1]
	v_mov_b32_e32 v41, v33
	s_waitcnt lgkmcnt(0)
	v_pk_add_f32 v[32:33], v[20:21], v[30:31] neg_lo:[0,1] neg_hi:[0,1]
	v_pk_add_f32 v[20:21], v[20:21], v[30:31]
	v_xor_b32_e32 v37, 0x80000000, v32
	v_pk_add_f32 v[26:27], v[6:7], v[20:21]
	v_pk_add_f32 v[6:7], v[6:7], v[20:21] neg_lo:[0,1] neg_hi:[0,1]
	v_mov_b32_e32 v36, v33
	v_pk_mul_f32 v[32:33], v[34:35], v[32:33] op_sel_hi:[0,1]
	v_pk_mul_f32 v[20:21], v[14:15], v[6:7] op_sel_hi:[0,1]
	v_pk_add_f32 v[12:13], v[12:13], v[12:13] op_sel:[0,1] op_sel_hi:[0,1] neg_lo:[0,1] neg_hi:[0,1]
	v_pk_fma_f32 v[8:9], v[8:9], v[36:37], v[32:33] op_sel_hi:[0,1,1] neg_lo:[0,0,1] neg_hi:[0,0,1]
	ds_write_b64 v5, v[26:27]
	v_pk_fma_f32 v[26:27], v[12:13], v[6:7], v[20:21] op_sel:[0,0,1] op_sel_hi:[1,1,0] neg_lo:[0,0,1] neg_hi:[0,0,1]
	v_pk_fma_f32 v[6:7], v[12:13], v[6:7], v[20:21] op_sel:[0,0,1] op_sel_hi:[1,1,0]
	s_cmp_lg_u32 s0, -2
	v_mov_b32_e32 v27, v7
	v_pk_add_f32 v[6:7], v[40:41], v[8:9]
	ds_write_b64 v15, v[26:27]
	ds_write_b64 v17, v[6:7]
	v_pk_add_f32 v[6:7], v[40:41], v[8:9] neg_lo:[0,1] neg_hi:[0,1]
	s_nop 0
	v_pk_mul_f32 v[8:9], v[14:15], v[6:7] op_sel_hi:[0,1]
	v_pk_fma_f32 v[14:15], v[12:13], v[6:7], v[8:9] op_sel:[0,0,1] op_sel_hi:[1,1,0] neg_lo:[0,0,1] neg_hi:[0,0,1]
	v_pk_fma_f32 v[6:7], v[12:13], v[6:7], v[8:9] op_sel:[0,0,1] op_sel_hi:[1,1,0]
	s_nop 0
	v_mov_b32_e32 v15, v7
	ds_write_b64 v19, v[14:15]
	s_cbranch_scc1 .LBB0_367
.Lfft_doneb_367:
	v_mov_b32_e32 v1, v215
	s_waitcnt lgkmcnt(0)
	s_barrier
	s_nop 0
	v_cmp_gt_i32_e32 vcc, s46, v1
	s_barrier
	s_and_saveexec_b64 s[0:1], vcc
	s_cbranch_execz .LBB0_376
	v_max_i32_e32 v2, 0xe00, v1
	v_sub_u32_e32 v2, v2, v1
	v_add_u32_e32 v3, 0x1ff, v2
	v_and_b32_e32 v2, 0x600, v3
	s_movk_i32 s10, 0x600
	v_cmp_ne_u32_e32 vcc, s10, v2
	v_mov_b32_e32 v2, v1
	s_and_saveexec_b64 s[10:11], vcc
	s_cbranch_execz .LBB0_373
	v_lshrrev_b32_e32 v2, 9, v3
	v_add_u32_e32 v2, 1, v2
	v_and_b32_e32 v2, 3, v2
	v_readlane_b32 s12, v254, 39
	v_sub_u32_e32 v5, 0, v2
	v_mov_b32_e32 v2, v1
	v_lshl_add_u32 v4, v1, 3, s12
	s_mov_b64 s[12:13], 0
